# v8 plus counted lgkmcnt waits in the RWKV producers forward-substitution block (five serial LDS round trips removed)
# speedup vs baseline: 1.0112x; 1.0018x over previous
; #define LAS __attribute__((address_space(3)))
; __device__ __forceinline__ f32x4 bf4(v2u u) { return (f32x4){bflo(u.x), bfhi(u.x), bflo(u.y), bfhi(u.y)}; }
; __device__ __forceinline__ float row16_sum(float x) { x += dpp_f<0xB1>(x); x += dpp_f<0x4E>(x); x += dpp_f<0x141>(x); x += dpp_f<0x140>(x); return x; }
; __device__ __forceinline__ void rw_scan(const bf16* R, const bf16* K, const bf16* V, const bf16* WM, const bf16* A, const float* k_k, const float* k_a, bf16* Y, LAS unsigned char* lds) {
;     ...
;                     LAS unsigned char* slot = lds + (cj % RW_NSLOT) * RWS_SLOT;
;                     f32x4 wv[4], kk[4], km[4], be[4], rr[4];
; #pragma unroll
;                     for (int j = 0; j < 4; ++j) {
;                         const f32x4 r = bf4(cu.r[j]), k = bf4(cu.k[j]), wm = bf4(cu.wm[j]), a = bf4(cu.a[j]);
;                         const f32x4 kr = k * kkc;
;                         const float n2 = row16_sum((kr[0] * kr[0] + kr[1] * kr[1]) + (kr[2] * kr[2] + kr[3] * kr[3]));
;                         const float inv = 1.0f / fmaxf(sqrtf(n2), 1e-12f);
;                         kk[j] = kr * inv; be[j] = kk[j] * a; km[j] = k * (1.0f + (a - 1.0f) * kac); wv[j] = 1.0f - wm; rr[j] = r;
;                     }
.LBB0_498:
	s_waitcnt vmcnt(21)
	v_lshlrev_b32_e32 v92, 16, v70
	v_and_b32_e32 v93, 0xffff0000, v70
	v_lshlrev_b32_e32 v94, 16, v71
	v_and_b32_e32 v95, 0xffff0000, v71
	v_pk_mul_f32 v[70:71], v[0:1], v[92:93]
	v_pk_mul_f32 v[72:73], v[2:3], v[94:95]
	v_lshlrev_b32_e32 v34, 16, v66
	v_and_b32_e32 v88, 0xffff0000, v66
	v_lshlrev_b32_e32 v89, 16, v67
	v_and_b32_e32 v90, 0xffff0000, v67
	v_pk_mul_f32 v[66:67], v[72:73], v[72:73]
	v_pk_mul_f32 v[82:83], v[70:71], v[70:71]
	v_sub_f32_e32 v103, 1.0, v90
	v_pk_mov_b32 v[86:87], v[82:83], v[66:67] op_sel:[1,0]
	v_mov_b32_e32 v83, v67
	v_pk_add_f32 v[66:67], v[86:87], v[82:83]
	v_lshlrev_b32_e32 v82, 16, v80
	v_and_b32_e32 v83, 0xffff0000, v80
	v_lshlrev_b32_e32 v90, 16, v81
	v_and_b32_e32 v91, 0xffff0000, v81
	v_lshlrev_b32_e32 v112, 16, v78
	v_and_b32_e32 v113, 0xffff0000, v78
	v_lshlrev_b32_e32 v114, 16, v79
	v_and_b32_e32 v115, 0xffff0000, v79
	v_pk_mul_f32 v[78:79], v[0:1], v[82:83]
	v_pk_mul_f32 v[80:81], v[2:3], v[90:91]
	v_sub_f32_e32 v101, 1.0, v88
	v_sub_f32_e32 v102, 1.0, v89
	v_pk_mul_f32 v[86:87], v[80:81], v[80:81]
	v_pk_mul_f32 v[88:89], v[78:79], v[78:79]
	v_sub_f32_e32 v100, 1.0, v34
	v_pk_mov_b32 v[110:111], v[88:89], v[86:87] op_sel:[1,0]
	v_mov_b32_e32 v89, v87
	v_pk_add_f32 v[86:87], v[110:111], v[88:89]
	s_mul_hi_u32 s68, s89, 0x38e38e39
	v_add_f32_e32 v34, v86, v87
	s_lshr_b32 s68, s68, 1
	s_mul_i32 s68, s68, 9
	v_add_f32_dpp v34, v34, v34 quad_perm:[1,0,3,2] row_mask:0xf bank_mask:0xf bound_ctrl:1
	s_sub_i32 s92, s89, s68
	v_lshlrev_b32_e32 v108, 16, v74
	v_add_f32_dpp v34, v34, v34 quad_perm:[2,3,0,1] row_mask:0xf bank_mask:0xf bound_ctrl:1
	v_and_b32_e32 v109, 0xffff0000, v74
	v_and_b32_e32 v111, 0xffff0000, v107
	v_add_f32_dpp v34, v34, v34 row_half_mirror row_mask:0xf bank_mask:0xf bound_ctrl:1
	v_lshlrev_b32_e32 v120, 16, v104
	v_and_b32_e32 v121, 0xffff0000, v104
	v_add_f32_dpp v34, v34, v34 row_mirror row_mask:0xf bank_mask:0xf bound_ctrl:1
	v_cmp_gt_f32_e32 vcc, s24, v34
	v_mul_f32_e32 v86, 0x4f800000, v34
	v_lshlrev_b32_e32 v122, 16, v105
	v_cndmask_b32_e32 v34, v34, v86, vcc
	v_sqrt_f32_e32 v86, v34
	v_and_b32_e32 v123, 0xffff0000, v105
	v_sub_f32_e32 v127, 1.0, v113
	v_sub_f32_e32 v126, 1.0, v112
	v_add_u32_e32 v87, -1, v86
	v_fma_f32 v88, -v87, v86, v34
	v_cmp_ge_f32_e64 s[68:69], 0, v88
	v_add_u32_e32 v88, 1, v86
	v_sub_f32_e32 v129, 1.0, v115
	v_cndmask_b32_e64 v87, v86, v87, s[68:69]
	v_fma_f32 v86, -v88, v86, v34
	v_cmp_lt_f32_e64 s[68:69], 0, v86
	v_sub_f32_e32 v128, 1.0, v114
	v_lshlrev_b32_e32 v116, 16, v98
	v_cndmask_b32_e64 v86, v87, v88, s[68:69]
	v_mul_f32_e32 v87, 0x37800000, v86
	v_cndmask_b32_e32 v86, v86, v87, vcc
	v_cmp_class_f32_e32 vcc, v34, v229
	v_and_b32_e32 v117, 0xffff0000, v98
	v_sub_f32_e32 v133, 1.0, v121
	v_cndmask_b32_e32 v34, v86, v34, vcc
	v_max_f32_e32 v34, 0x2b8cbccc, v34
	v_div_scale_f32 v86, s[68:69], v34, v34, 1.0
	v_rcp_f32_e32 v87, v86
	v_sub_f32_e32 v132, 1.0, v120
	v_lshlrev_b32_e32 v120, 16, v85
	v_and_b32_e32 v121, 0xffff0000, v85
	v_fma_f32 v88, -v86, v87, 1.0
	v_fmac_f32_e32 v87, v88, v87
	v_div_scale_f32 v88, vcc, 1.0, v34, 1.0
	v_mul_f32_e32 v89, v88, v87
	v_fma_f32 v110, -v86, v89, v88
	v_fmac_f32_e32 v89, v110, v87
	v_fma_f32 v86, -v86, v89, v88
	v_div_fmas_f32 v86, v86, v87, v89
	v_div_fixup_f32 v34, v86, v34, 1.0
	v_pk_mul_f32 v[88:89], v[78:79], v[34:35] op_sel_hi:[1,0]
	v_lshlrev_b32_e32 v110, 16, v107
	v_pk_mul_f32 v[78:79], v[88:89], v[108:109]
	v_pk_add_f32 v[108:109], v[108:109], -1.0 op_sel_hi:[1,0]
	v_pk_mul_f32 v[86:87], v[80:81], v[34:35] op_sel_hi:[1,0]
	v_pk_fma_f32 v[108:109], v[4:5], v[108:109], 1.0 op_sel_hi:[1,1,0]
	v_sub_f32_e32 v131, 1.0, v123
	v_pk_mul_f32 v[82:83], v[108:109], v[82:83]
	v_lshlrev_b32_e32 v108, 16, v106
	v_and_b32_e32 v109, 0xffff0000, v106
	v_pk_mul_f32 v[104:105], v[0:1], v[108:109]
	v_pk_mul_f32 v[106:107], v[2:3], v[110:111]
	v_pk_mul_f32 v[114:115], v[104:105], v[104:105]
	v_pk_mul_f32 v[112:113], v[106:107], v[106:107]
	v_sub_f32_e32 v130, 1.0, v122
	v_pk_mov_b32 v[118:119], v[114:115], v[112:113] op_sel:[1,0]
	v_mov_b32_e32 v115, v113
	v_pk_add_f32 v[112:113], v[118:119], v[114:115]
	v_and_b32_e32 v119, 0xffff0000, v84
	v_add_f32_e32 v34, v112, v113
	v_lshlrev_b32_e32 v136, 16, v10
	v_and_b32_e32 v137, 0xffff0000, v10
	v_add_f32_dpp v34, v34, v34 quad_perm:[1,0,3,2] row_mask:0xf bank_mask:0xf bound_ctrl:1
	v_lshlrev_b32_e32 v164, 16, v11
	v_and_b32_e32 v165, 0xffff0000, v11
	v_add_f32_dpp v34, v34, v34 quad_perm:[2,3,0,1] row_mask:0xf bank_mask:0xf bound_ctrl:1
	v_lshlrev_b32_e32 v10, 16, v8
	v_and_b32_e32 v11, 0xffff0000, v8
	v_add_f32_dpp v34, v34, v34 row_half_mirror row_mask:0xf bank_mask:0xf bound_ctrl:1
	v_lshlrev_b32_e32 v8, 16, v9
	v_and_b32_e32 v9, 0xffff0000, v9
	v_add_f32_dpp v34, v34, v34 row_mirror row_mask:0xf bank_mask:0xf bound_ctrl:1
	v_cmp_gt_f32_e32 vcc, s24, v34
	v_mul_f32_e32 v112, 0x4f800000, v34
	v_pk_mul_f32 v[166:167], v[100:101], v[126:127]
	v_cndmask_b32_e32 v34, v34, v112, vcc
	v_sqrt_f32_e32 v112, v34
	v_pk_mul_f32 v[132:133], v[166:167], v[132:133]
	v_add_f32_e32 v66, v66, v67
	s_mul_i32 s74, s92, 0x2c00
	v_add_u32_e32 v113, -1, v112
	v_fma_f32 v114, -v113, v112, v34
	v_cmp_ge_f32_e64 s[68:69], 0, v114
	v_add_u32_e32 v114, 1, v112
	v_add_f32_dpp v66, v66, v66 quad_perm:[1,0,3,2] row_mask:0xf bank_mask:0xf bound_ctrl:1
	v_cndmask_b32_e64 v113, v112, v113, s[68:69]
	v_fma_f32 v112, -v114, v112, v34
	v_cmp_lt_f32_e64 s[68:69], 0, v112
	v_add_f32_dpp v66, v66, v66 quad_perm:[2,3,0,1] row_mask:0xf bank_mask:0xf bound_ctrl:1
	s_waitcnt vmcnt(20)
; __device__ __forceinline__ f32x4 bf4(v2u u) { return (f32x4){bflo(u.x), bfhi(u.x), bflo(u.y), bfhi(u.y)}; }
; __device__ __forceinline__ float row16_sum(float x) { x += dpp_f<0xB1>(x); x += dpp_f<0x4E>(x); x += dpp_f<0x141>(x); x += dpp_f<0x140>(x); return x; }
; __device__ __forceinline__ void rw_scan(const bf16* R, const bf16* K, const bf16* V, const bf16* WM, const bf16* A, const float* k_k, const float* k_a, bf16* Y, LAS unsigned char* lds) {
;     ...
;                     for (int j = 0; j < 4; ++j) {
;                         const f32x4 r = bf4(cu.r[j]), k = bf4(cu.k[j]), wm = bf4(cu.wm[j]), a = bf4(cu.a[j]);
;                         const f32x4 kr = k * kkc;
;                         const float n2 = row16_sum((kr[0] * kr[0] + kr[1] * kr[1]) + (kr[2] * kr[2] + kr[3] * kr[3]));
;                         const float inv = 1.0f / fmaxf(sqrtf(n2), 1e-12f);
;                         kk[j] = kr * inv; be[j] = kk[j] * a; km[j] = k * (1.0f + (a - 1.0f) * kac); wv[j] = 1.0f - wm; rr[j] = r;
;                     }
;                     f32x4 g[4]; g[0] = wv[0]; g[1] = g[0] * wv[1]; g[2] = g[1] * wv[2]; g[3] = g[2] * wv[3];
;                     f32x4 pre = (f32x4){1.f, 1.f, 1.f, 1.f}, all = (f32x4){1.f, 1.f, 1.f, 1.f};
; #pragma unroll
;                     for (int x = 0; x < 4; ++x) {
;                         const float t0 = __shfl(g[3][x], fr), t1 = __shfl(g[3][x], 16 + fr), t2 = __shfl(g[3][x], 32 + fr), t3 = __shfl(g[3][x], 48 + fr);
;                         float p = 1.f; if (fq > 0) p *= t0; if (fq > 1) p *= t1; if (fq > 2) p *= t2;
;                         pre[x] = p; all[x] = (t0 * t1) * (t2 * t3);
;                     }
	v_and_b32_e32 v175, 0xffff0000, v33
	v_cndmask_b32_e64 v112, v113, v114, s[68:69]
	v_mul_f32_e32 v113, 0x37800000, v112
	v_cndmask_b32_e32 v112, v112, v113, vcc
	v_cmp_class_f32_e32 vcc, v34, v229
	v_add_f32_dpp v202, v66, v66 row_half_mirror row_mask:0xf bank_mask:0xf bound_ctrl:1
	s_add_i32 s74, s74, 0
	v_cndmask_b32_e32 v34, v112, v34, vcc
	v_max_f32_e32 v34, 0x2b8cbccc, v34
	v_div_scale_f32 v112, s[68:69], v34, v34, 1.0
	v_rcp_f32_e32 v113, v112
	v_mov_b32_dpp v203, v202 row_mirror row_mask:0xf bank_mask:0xf bound_ctrl:1
	v_add_u32_e32 v204, s74, v146
	v_fma_f32 v114, -v112, v113, 1.0
	v_fmac_f32_e32 v113, v114, v113
	v_div_scale_f32 v114, vcc, 1.0, v34, 1.0
	v_mul_f32_e32 v115, v114, v113
	v_fma_f32 v118, -v112, v115, v114
	v_fmac_f32_e32 v115, v118, v113
	v_fma_f32 v112, -v112, v115, v114
	v_div_fmas_f32 v112, v112, v113, v115
	v_div_fixup_f32 v34, v112, v34, 1.0
	v_pk_mul_f32 v[114:115], v[104:105], v[34:35] op_sel_hi:[1,0]
	v_lshlrev_b32_e32 v118, 16, v84
	v_pk_mul_f32 v[104:105], v[114:115], v[116:117]
	v_pk_add_f32 v[116:117], v[116:117], -1.0 op_sel_hi:[1,0]
	v_pk_mul_f32 v[84:85], v[0:1], v[118:119]
	v_pk_fma_f32 v[116:117], v[4:5], v[116:117], 1.0 op_sel_hi:[1,1,0]
	v_pk_mul_f32 v[124:125], v[84:85], v[84:85]
	v_pk_mul_f32 v[108:109], v[116:117], v[108:109]
	v_pk_mul_f32 v[116:117], v[2:3], v[120:121]
	v_pk_mul_f32 v[112:113], v[106:107], v[34:35] op_sel_hi:[1,0]
	v_pk_mul_f32 v[122:123], v[116:117], v[116:117]
	v_lshlrev_b32_e32 v74, 16, v75
	v_pk_mov_b32 v[134:135], v[124:125], v[122:123] op_sel:[1,0]
	v_mov_b32_e32 v125, v123
	v_pk_add_f32 v[122:123], v[134:135], v[124:125]
	v_and_b32_e32 v75, 0xffff0000, v75
	v_add_f32_e32 v34, v122, v123
	v_pk_mul_f32 v[80:81], v[86:87], v[74:75]
	v_pk_add_f32 v[74:75], v[74:75], -1.0 op_sel_hi:[1,0]
	v_add_f32_dpp v34, v34, v34 quad_perm:[1,0,3,2] row_mask:0xf bank_mask:0xf bound_ctrl:1
	v_pk_fma_f32 v[74:75], v[6:7], v[74:75], 1.0 op_sel_hi:[1,1,0]
	v_lshlrev_b32_e32 v66, 16, v68
	v_add_f32_dpp v34, v34, v34 quad_perm:[2,3,0,1] row_mask:0xf bank_mask:0xf bound_ctrl:1
	v_pk_mul_f32 v[90:91], v[74:75], v[90:91]
	v_and_b32_e32 v67, 0xffff0000, v68
	v_add_f32_dpp v34, v34, v34 row_half_mirror row_mask:0xf bank_mask:0xf bound_ctrl:1
	v_lshlrev_b32_e32 v68, 16, v69
	v_and_b32_e32 v69, 0xffff0000, v69
	v_add_f32_dpp v34, v34, v34 row_mirror row_mask:0xf bank_mask:0xf bound_ctrl:1
	v_cmp_gt_f32_e32 vcc, s24, v34
	v_mul_f32_e32 v122, 0x4f800000, v34
	v_lshlrev_b32_e32 v98, 16, v99
	v_cndmask_b32_e32 v34, v34, v122, vcc
	v_sqrt_f32_e32 v122, v34
	v_and_b32_e32 v99, 0xffff0000, v99
	v_pk_mul_f32 v[106:107], v[112:113], v[98:99]
	v_pk_add_f32 v[98:99], v[98:99], -1.0 op_sel_hi:[1,0]
	v_add_u32_e32 v123, -1, v122
	v_fma_f32 v124, -v123, v122, v34
	v_cmp_ge_f32_e64 s[68:69], 0, v124
	v_add_u32_e32 v124, 1, v122
	v_pk_fma_f32 v[98:99], v[6:7], v[98:99], 1.0 op_sel_hi:[1,1,0]
	v_cndmask_b32_e64 v123, v122, v123, s[68:69]
	v_fma_f32 v122, -v124, v122, v34
	v_cmp_lt_f32_e64 s[68:69], 0, v122
	v_pk_mul_f32 v[110:111], v[98:99], v[110:111]
	v_lshlrev_b32_e32 v74, 16, v76
	v_cndmask_b32_e64 v122, v123, v124, s[68:69]
	v_mul_f32_e32 v123, 0x37800000, v122
	v_cndmask_b32_e32 v122, v122, v123, vcc
	v_cmp_class_f32_e32 vcc, v34, v229
	v_and_b32_e32 v75, 0xffff0000, v76
	v_lshlrev_b32_e32 v76, 16, v77
	v_cndmask_b32_e32 v34, v122, v34, vcc
	v_max_f32_e32 v34, 0x2b8cbccc, v34
	v_div_scale_f32 v122, s[68:69], v34, v34, 1.0
	v_rcp_f32_e32 v123, v122
	v_and_b32_e32 v77, 0xffff0000, v77
	v_lshlrev_b32_e32 v98, 16, v96
	v_and_b32_e32 v99, 0xffff0000, v96
	v_fma_f32 v124, -v122, v123, 1.0
	v_fmac_f32_e32 v123, v124, v123
	v_div_scale_f32 v124, vcc, 1.0, v34, 1.0
	v_mul_f32_e32 v125, v124, v123
	v_fma_f32 v134, -v122, v125, v124
	v_fmac_f32_e32 v125, v134, v123
	v_fma_f32 v122, -v122, v125, v124
	v_div_fmas_f32 v122, v122, v123, v125
	v_div_fixup_f32 v34, v122, v34, 1.0
	v_pk_mul_f32 v[122:123], v[116:117], v[34:35] op_sel_hi:[1,0]
	v_pk_mul_f32 v[124:125], v[84:85], v[34:35] op_sel_hi:[1,0]
	v_pk_mul_f32 v[116:117], v[122:123], v[8:9]
	v_pk_add_f32 v[8:9], v[8:9], -1.0 op_sel_hi:[1,0]
	v_pk_mul_f32 v[84:85], v[124:125], v[10:11]
	v_pk_add_f32 v[10:11], v[10:11], -1.0 op_sel_hi:[1,0]
	v_pk_fma_f32 v[8:9], v[6:7], v[8:9], 1.0 op_sel_hi:[1,1,0]
	v_pk_fma_f32 v[10:11], v[4:5], v[10:11], 1.0 op_sel_hi:[1,1,0]
	v_pk_mul_f32 v[120:121], v[8:9], v[120:121]
	v_sub_f32_e32 v9, 1.0, v137
	v_sub_f32_e32 v8, 1.0, v136
	v_pk_mul_f32 v[118:119], v[10:11], v[118:119]
	v_sub_f32_e32 v11, 1.0, v165
	v_sub_f32_e32 v10, 1.0, v164
	v_pk_mul_f32 v[164:165], v[102:103], v[128:129]
	v_pk_mul_f32 v[128:129], v[132:133], v[8:9]
	v_or_b32_e32 v8, v232, v24
	v_lshlrev_b32_e32 v34, 2, v8
	v_or_b32_e32 v8, v232, v143
	v_lshlrev_b32_e32 v171, 2, v8
	v_or_b32_e32 v8, v232, v144
	v_lshlrev_b32_e32 v173, 2, v8
	v_or_b32_e32 v8, v232, v145
	v_pk_mul_f32 v[134:135], v[164:165], v[130:131]
	v_lshlrev_b32_e32 v174, 2, v8
	ds_bpermute_b32 v8, v34, v128
	v_pk_mul_f32 v[126:127], v[134:135], v[10:11]
	ds_bpermute_b32 v10, v171, v128
	ds_bpermute_b32 v136, v173, v128
	ds_bpermute_b32 v9, v34, v129
	ds_bpermute_b32 v168, v174, v128
	ds_bpermute_b32 v11, v171, v129
	ds_bpermute_b32 v169, v173, v129
	ds_bpermute_b32 v137, v174, v129
	s_waitcnt lgkmcnt(7)
	v_cndmask_b32_e64 v130, v8, 1.0, s[42:43]
	s_waitcnt lgkmcnt(6)
	v_mul_f32_e32 v131, v130, v10
	v_cndmask_b32_e64 v130, v130, v131, s[44:45]
	s_waitcnt lgkmcnt(5)
	v_mul_f32_e32 v131, v130, v136
	v_cndmask_b32_e64 v130, v130, v131, s[46:47]
	s_waitcnt lgkmcnt(4)
	v_cndmask_b32_e64 v131, v9, 1.0, s[42:43]
	s_waitcnt lgkmcnt(2)
	v_mul_f32_e32 v170, v131, v11
	v_pk_mul_f32 v[8:9], v[8:9], v[10:11]
	s_waitcnt lgkmcnt(0)
; #define LAS __attribute__((address_space(3)))
; __device__ __forceinline__ void rw_scan(const bf16* R, const bf16* K, const bf16* V, const bf16* WM, const bf16* A, const float* k_k, const float* k_a, bf16* Y, LAS unsigned char* lds) {
;     ...
;                         const f32x4 r = bf4(cu.r[j]), k = bf4(cu.k[j]), wm = bf4(cu.wm[j]), a = bf4(cu.a[j]);
;                         const f32x4 kr = k * kkc;
;                         const float n2 = row16_sum((kr[0] * kr[0] + kr[1] * kr[1]) + (kr[2] * kr[2] + kr[3] * kr[3]));
;                         const float inv = 1.0f / fmaxf(sqrtf(n2), 1e-12f);
;                         kk[j] = kr * inv; be[j] = kk[j] * a; km[j] = k * (1.0f + (a - 1.0f) * kac); wv[j] = 1.0f - wm; rr[j] = r;
;                     }
;                     f32x4 g[4]; g[0] = wv[0]; g[1] = g[0] * wv[1]; g[2] = g[1] * wv[2]; g[3] = g[2] * wv[3];
;                     f32x4 pre = (f32x4){1.f, 1.f, 1.f, 1.f}, all = (f32x4){1.f, 1.f, 1.f, 1.f};
; #pragma unroll
;                     for (int x = 0; x < 4; ++x) {
;                         const float t0 = __shfl(g[3][x], fr), t1 = __shfl(g[3][x], 16 + fr), t2 = __shfl(g[3][x], 32 + fr), t3 = __shfl(g[3][x], 48 + fr);
;                         float p = 1.f; if (fq > 0) p *= t0; if (fq > 1) p *= t1; if (fq > 2) p *= t2;
;                         pre[x] = p; all[x] = (t0 * t1) * (t2 * t3);
;                     }
;                     unsigned kgp[4][2], bgp[4][2], abp[4][2];
;                     float kgt[4][4], bgt[4][4], abt[4][4];
; #pragma unroll
;                     for (int j = 0; j < 4; ++j) {
;                         const f32x4 Gs = pre * g[j], Gm = j ? pre * g[j - 1] : pre;
;                         f32x4 ginv; ginv[0] = __builtin_amdgcn_rcpf(Gs[0]); ginv[1] = __builtin_amdgcn_rcpf(Gs[1]); ginv[2] = __builtin_amdgcn_rcpf(Gs[2]); ginv[3] = __builtin_amdgcn_rcpf(Gs[3]);
;                         const f32x4 alb = kk[j] * Gm, rb = rr[j] * Gs, bet = be[j] * ginv, ktl = km[j] * ginv;
;                         const int s = 4 * fq + j;
;                         v2u o;
;                         o.x = pk2(alb[0], alb[1]); o.y = pk2(alb[2], alb[3]); *(LAS v2u*)(tmp + RWT_AB + s * 128 + 8 * fr) = o;
;                         o.x = pk2(bet[0], bet[1]); o.y = pk2(bet[2], bet[3]); *(LAS v2u*)(tmp + RWT_BT + s * 128 + 8 * fr) = o;
	v_pk_mul_f32 v[10:11], v[168:169], v[136:137]
	v_cndmask_b32_e64 v131, v131, v170, s[44:45]
	v_pk_mul_f32 v[8:9], v[8:9], v[10:11]
	ds_bpermute_b32 v10, v34, v126
	ds_bpermute_b32 v168, v171, v126
	v_mul_f32_e32 v170, v131, v169
	v_cndmask_b32_e64 v131, v131, v170, s[46:47]
	ds_bpermute_b32 v170, v173, v126
	ds_bpermute_b32 v11, v34, v127
	ds_bpermute_b32 v172, v174, v126
	ds_bpermute_b32 v169, v171, v127
	ds_bpermute_b32 v173, v173, v127
	ds_bpermute_b32 v171, v174, v127
	s_waitcnt lgkmcnt(7)
	v_cndmask_b32_e64 v34, v10, 1.0, s[42:43]
	s_waitcnt lgkmcnt(6)
	v_mul_f32_e32 v136, v34, v168
	v_cndmask_b32_e64 v34, v34, v136, s[44:45]
	s_waitcnt lgkmcnt(5)
	v_mul_f32_e32 v136, v34, v170
	v_cndmask_b32_e64 v136, v34, v136, s[46:47]
	s_waitcnt lgkmcnt(4)
	v_cndmask_b32_e64 v34, v11, 1.0, s[42:43]
	s_waitcnt lgkmcnt(2)
	v_mul_f32_e32 v137, v34, v169
	v_pk_mul_f32 v[10:11], v[10:11], v[168:169]
	s_waitcnt lgkmcnt(0)
	v_pk_mul_f32 v[168:169], v[172:173], v[170:171]
	v_cndmask_b32_e64 v34, v34, v137, s[44:45]
	v_pk_mul_f32 v[10:11], v[10:11], v[168:169]
	v_lshlrev_b32_e32 v168, 16, v64
	v_and_b32_e32 v169, 0xffff0000, v64
	v_mul_f32_e32 v137, v34, v173
	v_pk_add_f32 v[170:171], v[168:169], -1.0 op_sel_hi:[1,0]
	v_cndmask_b32_e64 v137, v34, v137, s[46:47]
	v_pk_fma_f32 v[170:171], v[4:5], v[170:171], 1.0 op_sel_hi:[1,1,0]
	v_add_f32_e32 v34, v202, v203
	v_pk_mul_f32 v[92:93], v[170:171], v[92:93]
	v_cmp_gt_f32_e32 vcc, s24, v34
	v_mul_f32_e32 v170, 0x4f800000, v34
	v_lshlrev_b32_e32 v64, 16, v65
	v_cndmask_b32_e32 v34, v34, v170, vcc
	v_sqrt_f32_e32 v170, v34
	v_and_b32_e32 v65, 0xffff0000, v65
	v_pk_add_f32 v[172:173], v[64:65], -1.0 op_sel_hi:[1,0]
	v_pk_mul_f32 v[102:103], v[102:103], v[136:137]
	v_pk_fma_f32 v[172:173], v[6:7], v[172:173], 1.0 op_sel_hi:[1,1,0]
	v_add_u32_e32 v171, -1, v170
	v_pk_mul_f32 v[94:95], v[172:173], v[94:95]
	v_fma_f32 v172, -v171, v170, v34
	v_cmp_ge_f32_e64 s[68:69], 0, v172
	v_add_u32_e32 v172, 1, v170
	v_pk_mul_f32 v[100:101], v[100:101], v[130:131]
	v_cndmask_b32_e64 v171, v170, v171, s[68:69]
	v_fma_f32 v170, -v172, v170, v34
	v_cmp_lt_f32_e64 s[68:69], 0, v170
	v_rcp_f32_e32 v176, v100
	v_rcp_f32_e32 v177, v101
	v_cndmask_b32_e64 v170, v171, v172, s[68:69]
	v_mul_f32_e32 v171, 0x37800000, v170
	v_cndmask_b32_e32 v170, v170, v171, vcc
	v_cmp_class_f32_e32 vcc, v34, v229
	v_rcp_f32_e32 v178, v102
	v_rcp_f32_e32 v179, v103
	v_cndmask_b32_e32 v34, v170, v34, vcc
	v_max_f32_e32 v34, 0x2b8cbccc, v34
	v_div_scale_f32 v170, s[68:69], v34, v34, 1.0
	v_rcp_f32_e32 v171, v170
	v_pk_mul_f32 v[94:95], v[94:95], v[178:179]
	v_pk_mul_f32 v[92:93], v[92:93], v[176:177]
	v_pk_mul_f32 v[86:87], v[86:87], v[102:103]
	v_fma_f32 v172, -v170, v171, 1.0
	v_fmac_f32_e32 v171, v172, v171
	v_div_scale_f32 v172, vcc, 1.0, v34, 1.0
	v_mul_f32_e32 v173, v172, v171
	v_fma_f32 v174, -v170, v173, v172
	v_fmac_f32_e32 v173, v174, v171
	v_fma_f32 v170, -v170, v173, v172
	v_div_fmas_f32 v170, v170, v171, v173
	v_div_fixup_f32 v34, v170, v34, 1.0
	v_pk_mul_f32 v[72:73], v[72:73], v[34:35] op_sel_hi:[1,0]
	v_pk_mul_f32 v[70:71], v[70:71], v[34:35] op_sel_hi:[1,0]
	v_pk_mul_f32 v[170:171], v[72:73], v[64:65]
	v_pk_mul_f32 v[168:169], v[70:71], v[168:169]
	v_lshlrev_b32_e32 v172, 16, v32
	v_and_b32_e32 v173, 0xffff0000, v32
	v_lshlrev_b32_e32 v174, 16, v33
	v_pk_mul_f32 v[32:33], v[72:73], v[136:137]
	v_pk_mul_f32 v[64:65], v[70:71], v[130:131]
	v_pk_mul_f32 v[170:171], v[170:171], v[178:179]
	v_pk_mul_f32 v[168:169], v[168:169], v[176:177]
	v_pk_mul_f32 v[70:71], v[102:103], v[174:175]
	v_pk_mul_f32 v[72:73], v[100:101], v[172:173]
	v_cvt_pk_bf16_f32 v172, v64, v65
	v_cvt_pk_bf16_f32 v173, v32, v33
	v_add_u32_e32 v34, v147, v154
	v_cvt_pk_bf16_f32 v174, v168, v169
	v_cvt_pk_bf16_f32 v175, v170, v171
	ds_write2st64_b64 v34, v[172:173], v[174:175] offset1:4
	v_cvt_pk_bf16_f32 v172, v92, v93
	v_cvt_pk_bf16_f32 v173, v94, v95
	ds_write_b64 v34, v[172:173] offset:4096
	v_cvt_pk_bf16_f32 v72, v72, v73
	v_cvt_pk_bf16_f32 v73, v70, v71
	v_add_u32_e32 v34, v204, v154
	ds_write_b64 v34, v[72:73] offset:2048
	v_pk_mul_f32 v[70:71], v[164:165], v[136:137]
	v_pk_mul_f32 v[72:73], v[166:167], v[130:131]
	v_rcp_f32_e32 v166, v70
	v_rcp_f32_e32 v164, v72
	v_rcp_f32_e32 v165, v73
	v_rcp_f32_e32 v167, v71
	v_pk_mul_f32 v[88:89], v[88:89], v[100:101]
	v_cvt_pk_bf16_f32 v101, v86, v87
	v_pk_mul_f32 v[78:79], v[78:79], v[164:165]
	v_pk_mul_f32 v[80:81], v[80:81], v[166:167]
	v_pk_mul_f32 v[90:91], v[90:91], v[166:167]
	v_pk_mul_f32 v[82:83], v[82:83], v[164:165]
	v_cvt_pk_bf16_f32 v100, v88, v89
	v_add_u32_e32 v34, v147, v155
	v_cvt_pk_bf16_f32 v102, v78, v79
	v_cvt_pk_bf16_f32 v103, v80, v81
	v_pk_mul_f32 v[68:69], v[70:71], v[68:69]
	v_pk_mul_f32 v[66:67], v[72:73], v[66:67]
	ds_write2st64_b64 v34, v[100:101], v[102:103] offset1:4
	v_cvt_pk_bf16_f32 v100, v82, v83
	v_cvt_pk_bf16_f32 v101, v90, v91
	ds_write_b64 v34, v[100:101] offset:4096
	v_cvt_pk_bf16_f32 v66, v66, v67
	v_cvt_pk_bf16_f32 v67, v68, v69
	v_add_u32_e32 v34, v204, v155
	ds_write_b64 v34, v[66:67] offset:2048
	v_mov_b32_e32 v66, v92
	v_mov_b32_e32 v67, v82
	v_mov_b32_e32 v82, v93
	v_mov_b32_e32 v92, v94
	v_mov_b32_e32 v93, v90
	v_mov_b32_e32 v90, v95
	v_pk_mul_f32 v[94:95], v[134:135], v[136:137]
	v_pk_mul_f32 v[102:103], v[132:133], v[130:131]
	v_rcp_f32_e32 v134, v94
	v_rcp_f32_e32 v132, v102
	v_rcp_f32_e32 v133, v103
	v_rcp_f32_e32 v135, v95
	v_pk_mul_f32 v[70:71], v[112:113], v[70:71]
	v_pk_mul_f32 v[72:73], v[114:115], v[72:73]
	v_pk_mul_f32 v[104:105], v[104:105], v[132:133]
	v_pk_mul_f32 v[106:107], v[106:107], v[134:135]
	v_pk_mul_f32 v[110:111], v[110:111], v[134:135]
; #define LAS __attribute__((address_space(3)))
; __device__ __forceinline__ void rw_scan(const bf16* R, const bf16* K, const bf16* V, const bf16* WM, const bf16* A, const float* k_k, const float* k_a, bf16* Y, LAS unsigned char* lds) {
;     ...
;                         o.x = pk2(alb[0], alb[1]); o.y = pk2(alb[2], alb[3]); *(LAS v2u*)(tmp + RWT_AB + s * 128 + 8 * fr) = o;
;                         o.x = pk2(bet[0], bet[1]); o.y = pk2(bet[2], bet[3]); *(LAS v2u*)(tmp + RWT_BT + s * 128 + 8 * fr) = o;
;                         o.x = pk2(ktl[0], ktl[1]); o.y = pk2(ktl[2], ktl[3]); *(LAS v2u*)(tmp + RWT_KT + s * 128 + 8 * fr) = o;
;                         o.x = pk2(rb[0], rb[1]); o.y = pk2(rb[2], rb[3]); *(LAS v2u*)(slot + RWS_RB + s * 128 + 8 * fr) = o;
; #pragma unroll
;                         for (int x = 0; x < 4; ++x) { kgt[x][j] = ktl[x] * all[x]; bgt[x][j] = -(bet[x] * all[x]); abt[x][j] = alb[x]; }
;                     }
; #pragma unroll
;                     for (int x = 0; x < 4; ++x) {
;                         const int kch = 4 * fr + x;
;                         v2u o;
;                         o.x = pk2(kgt[x][0], kgt[x][1]); o.y = pk2(kgt[x][2], kgt[x][3]); *(LAS v2u*)(slot + RWS_KGT + rwz(kch) * 32 + 8 * fq) = o;
;                         o.x = pk2(bgt[x][0], bgt[x][1]); o.y = pk2(bgt[x][2], bgt[x][3]); *(LAS v2u*)(slot + RWS_BGT + rwz(kch) * 32 + 8 * fq) = o;
;                         o.x = pk2(abt[x][0], abt[x][1]); o.y = pk2(abt[x][2], abt[x][3]); *(LAS v2u*)(tmp + RWT_ABT + rwz(kch) * 32 + 8 * fq) = o;
;                     }
;                     if (fq == 0) *(LAS f32x4*)(slot + RWS_G15 + 16 * fr) = all;
;                     const unsigned vlo = (unsigned)cu.v[0] | ((unsigned)cu.v[1] << 16), vhi = (unsigned)cu.v[2] | ((unsigned)cu.v[3] << 16);
;                     { v2u o; o.x = vlo; o.y = vhi; *(LAS v2u*)(slot + RWS_VCI + 8 * lane) = o; }
;                     LDS_WAIT(); asm volatile("" ::: "memory");
;                     f32x4 nac = (f32x4){0.f, 0.f, 0.f, 0.f}, kat = nac, krt = nac, nrt = nac;
; #pragma unroll
;                     for (int p = 0; p < 2; ++p) {
;                         const int kb = (32 * p + 8 * fq) * 2;
;                         const bf16x8 oAB = lds_op16(tmp + RWT_AB, fr, kb), oBT = lds_op16(tmp + RWT_BT, fr, kb), oKT = lds_op16(tmp + RWT_KT, fr, kb), oRB = lds_op16(slot + RWS_RB, fr, kb);
	v_pk_mul_f32 v[108:109], v[108:109], v[132:133]
	v_cvt_pk_bf16_f32 v112, v72, v73
	v_cvt_pk_bf16_f32 v113, v70, v71
	v_add_u32_e32 v34, v147, v156
	v_cvt_pk_bf16_f32 v114, v104, v105
	v_cvt_pk_bf16_f32 v115, v106, v107
	v_pk_mul_f32 v[76:77], v[94:95], v[76:77]
	v_pk_mul_f32 v[74:75], v[102:103], v[74:75]
	ds_write2st64_b64 v34, v[112:113], v[114:115] offset1:4
	v_cvt_pk_bf16_f32 v112, v108, v109
	v_cvt_pk_bf16_f32 v113, v110, v111
	ds_write_b64 v34, v[112:113] offset:4096
	v_cvt_pk_bf16_f32 v74, v74, v75
	v_cvt_pk_bf16_f32 v75, v76, v77
	v_add_u32_e32 v34, v204, v156
	ds_write_b64 v34, v[74:75] offset:2048
	v_pk_mul_f32 v[74:75], v[126:127], v[136:137]
	v_pk_mul_f32 v[76:77], v[128:129], v[130:131]
	v_rcp_f32_e32 v114, v74
	v_rcp_f32_e32 v112, v76
	v_rcp_f32_e32 v113, v77
	v_rcp_f32_e32 v115, v75
	v_lshlrev_b32_e32 v96, 16, v97
	v_and_b32_e32 v97, 0xffff0000, v97
	v_pk_mul_f32 v[94:95], v[122:123], v[94:95]
	v_pk_mul_f32 v[102:103], v[124:125], v[102:103]
	v_pk_mul_f32 v[74:75], v[74:75], v[96:97]
	v_pk_mul_f32 v[96:97], v[116:117], v[114:115]
	v_pk_mul_f32 v[84:85], v[84:85], v[112:113]
	v_pk_mul_f32 v[76:77], v[76:77], v[98:99]
	v_pk_mul_f32 v[98:99], v[120:121], v[114:115]
	v_pk_mul_f32 v[112:113], v[118:119], v[112:113]
	v_cvt_pk_bf16_f32 v114, v102, v103
	v_cvt_pk_bf16_f32 v115, v94, v95
	v_add_u32_e32 v34, v147, v157
	v_cvt_pk_bf16_f32 v116, v84, v85
	v_cvt_pk_bf16_f32 v117, v96, v97
	ds_write2st64_b64 v34, v[114:115], v[116:117] offset1:4
	v_cvt_pk_bf16_f32 v114, v112, v113
	v_cvt_pk_bf16_f32 v115, v98, v99
	ds_write_b64 v34, v[114:115] offset:4096
	v_cvt_pk_bf16_f32 v76, v76, v77
	v_cvt_pk_bf16_f32 v77, v74, v75
	v_add_u32_e32 v34, v204, v157
	v_mov_b32_e32 v68, v168
	v_mov_b32_e32 v69, v78
	ds_write_b64 v34, v[76:77] offset:2048
	v_mov_b32_e32 v74, v108
	v_mov_b32_e32 v75, v112
	v_mov_b32_e32 v76, v104
	v_mov_b32_e32 v77, v84
	v_pk_mul_f32 v[66:67], v[8:9], v[66:67] op_sel_hi:[0,1]
	v_pk_mul_f32 v[68:69], v[68:69], v[8:9] op_sel_hi:[1,0] neg_lo:[0,1] neg_hi:[0,1]
	v_pk_mul_f32 v[74:75], v[8:9], v[74:75] op_sel_hi:[0,1]
	v_pk_mul_f32 v[76:77], v[76:77], v[8:9] op_sel_hi:[1,0] neg_lo:[0,1] neg_hi:[0,1]
	v_add_u32_e32 v34, s74, v139
	v_mov_b32_e32 v78, v169
	v_mov_b32_e32 v112, v109
	v_mov_b32_e32 v84, v105
	v_cvt_pk_bf16_f32 v66, v66, v67
	v_cvt_pk_bf16_f32 v67, v74, v75
	v_add_u32_e32 v74, v34, v158
	v_cvt_pk_bf16_f32 v68, v68, v69
	v_cvt_pk_bf16_f32 v69, v76, v77
	v_pk_mul_f32 v[82:83], v[8:9], v[82:83] op_sel:[1,0]
	v_pk_mul_f32 v[78:79], v[78:79], v[8:9] op_sel:[0,1] neg_lo:[0,1] neg_hi:[0,1]
	v_pk_mul_f32 v[108:109], v[8:9], v[112:113] op_sel:[1,0]
	v_pk_mul_f32 v[84:85], v[84:85], v[8:9] op_sel:[0,1] neg_lo:[0,1] neg_hi:[0,1]
	ds_write2st64_b64 v74, v[66:67], v[68:69] offset0:8 offset1:12
	v_cvt_pk_bf16_f32 v66, v64, v88
	v_cvt_pk_bf16_f32 v67, v72, v102
	v_add_u32_e32 v64, v148, v158
	v_mov_b32_e32 v100, v170
	v_mov_b32_e32 v101, v80
	v_mov_b32_e32 v104, v110
	v_mov_b32_e32 v105, v98
	v_mov_b32_e32 v112, v106
	v_mov_b32_e32 v113, v96
	ds_write_b64 v64, v[66:67] offset:6144
	v_cvt_pk_bf16_f32 v66, v82, v83
	v_cvt_pk_bf16_f32 v67, v108, v109
	v_add_u32_e32 v64, v34, v159
	v_cvt_pk_bf16_f32 v68, v78, v79
	v_cvt_pk_bf16_f32 v69, v84, v85
	v_pk_mul_f32 v[92:93], v[10:11], v[92:93] op_sel_hi:[0,1]
	v_pk_mul_f32 v[100:101], v[100:101], v[10:11] op_sel_hi:[1,0] neg_lo:[0,1] neg_hi:[0,1]
	v_pk_mul_f32 v[104:105], v[10:11], v[104:105] op_sel_hi:[0,1]
	v_pk_mul_f32 v[112:113], v[112:113], v[10:11] op_sel_hi:[1,0] neg_lo:[0,1] neg_hi:[0,1]
	ds_write2st64_b64 v64, v[66:67], v[68:69] offset0:8 offset1:12
	v_cvt_pk_bf16_f32 v64, v65, v89
	v_cvt_pk_bf16_f32 v65, v73, v103
	v_add_u32_e32 v66, v148, v159
	v_mov_b32_e32 v80, v171
	v_mov_b32_e32 v98, v111
	v_mov_b32_e32 v96, v107
	ds_write_b64 v66, v[64:65] offset:6144
	v_cvt_pk_bf16_f32 v64, v92, v93
	v_cvt_pk_bf16_f32 v65, v104, v105
	v_add_u32_e32 v68, v34, v160
	v_cvt_pk_bf16_f32 v66, v100, v101
	v_cvt_pk_bf16_f32 v67, v112, v113
	v_pk_mul_f32 v[90:91], v[10:11], v[90:91] op_sel:[1,0]
	v_pk_mul_f32 v[80:81], v[80:81], v[10:11] op_sel:[0,1] neg_lo:[0,1] neg_hi:[0,1]
	v_pk_mul_f32 v[98:99], v[10:11], v[98:99] op_sel:[1,0]
	v_pk_mul_f32 v[96:97], v[96:97], v[10:11] op_sel:[0,1] neg_lo:[0,1] neg_hi:[0,1]
	ds_write2st64_b64 v68, v[64:65], v[66:67] offset0:8 offset1:12
	v_cvt_pk_bf16_f32 v64, v32, v86
	v_cvt_pk_bf16_f32 v65, v70, v94
	v_add_u32_e32 v32, v148, v160
	ds_write_b64 v32, v[64:65] offset:6144
	v_cvt_pk_bf16_f32 v64, v90, v91
	v_cvt_pk_bf16_f32 v65, v98, v99
	v_add_u32_e32 v32, v34, v161
	v_cvt_pk_bf16_f32 v66, v80, v81
	v_cvt_pk_bf16_f32 v67, v96, v97
	ds_write2st64_b64 v32, v[64:65], v[66:67] offset0:8 offset1:12
	v_cvt_pk_bf16_f32 v32, v33, v87
	v_cvt_pk_bf16_f32 v33, v71, v95
	v_add_u32_e32 v34, v148, v161
	ds_write_b64 v34, v[32:33] offset:6144
	s_and_saveexec_b64 s[68:69], s[42:43]
	v_add_u32_e32 v32, s74, v149
	ds_write_b128 v32, v[8:11] offset:8192
	s_or_b64 exec, exec, s[68:69]
	v_lshlrev_b32_e32 v8, 16, v201
	v_lshlrev_b32_e32 v9, 16, v35
	v_or_b32_sdwa v8, v8, v200 dst_sel:DWORD dst_unused:UNUSED_PAD src0_sel:DWORD src1_sel:WORD_0
	v_or_b32_sdwa v9, v9, v199 dst_sel:DWORD dst_unused:UNUSED_PAD src0_sel:DWORD src1_sel:WORD_0
	v_add_u32_e32 v10, s74, v140
	ds_write_b64 v10, v[8:9] offset:10496
	ds_read_b128 v[32:35], v194 offset:2048
	ds_read_b128 v[64:67], v194
	ds_read_b128 v[68:71], v194 offset:64
	ds_read_b128 v[72:75], v194 offset:2112
	ds_read_b128 v[80:83], v194 offset:4096
	ds_read_b128 v[84:87], v194 offset:4160
	v_add3_u32 v10, s74, v138, v141
	ds_read_b128 v[88:91], v10 offset:2048
	ds_read_b128 v[92:95], v10 offset:2112
	s_waitcnt lgkmcnt(6)
; #define LAS __attribute__((address_space(3)))
; #define LDS_WAIT() asm volatile("s_waitcnt lgkmcnt(0)" ::: "memory")
; __device__ __forceinline__ unsigned pk2(float lo, float hi) { const f32x2_t v = {lo, hi}; const bf16x2_t b = __builtin_convertvector(v, bf16x2_t); return __builtin_bit_cast(unsigned, b); }
; __device__ __forceinline__ void rw_scan(const bf16* R, const bf16* K, const bf16* V, const bf16* WM, const bf16* A, const float* k_k, const float* k_a, bf16* Y, LAS unsigned char* lds) {
;     ...
;                     for (int p = 0; p < 2; ++p) {
;                         const int kb = (32 * p + 8 * fq) * 2;
;                         const bf16x8 oAB = lds_op16(tmp + RWT_AB, fr, kb), oBT = lds_op16(tmp + RWT_BT, fr, kb), oKT = lds_op16(tmp + RWT_KT, fr, kb), oRB = lds_op16(slot + RWS_RB, fr, kb);
;                         nac = __builtin_amdgcn_mfma_f32_16x16x32_bf16(oBT, oAB, nac, 0, 0, 0);
;                         kat = __builtin_amdgcn_mfma_f32_16x16x32_bf16(oKT, oAB, kat, 0, 0, 0);
;                         krt = __builtin_amdgcn_mfma_f32_16x16x32_bf16(oKT, oRB, krt, 0, 0, 0);
;                         nrt = __builtin_amdgcn_mfma_f32_16x16x32_bf16(oBT, oRB, nrt, 0, 0, 0);
;                     }
; #pragma unroll
;                     for (int i = 0; i < 4; ++i) { const int rr_ = 4 * fq + i;
;                         if (rr_ >= fr) { nac[i] = 0.f; kat[i] = 0.f; }
;                         if (rr_ > fr) { krt[i] = 0.f; nrt[i] = 0.f; } }
;                     { u32x4_t o; o.x = pk2(krt[0], krt[1]); o.y = pk2(krt[2], krt[3]); o.z = pk2(-nrt[0], -nrt[1]); o.w = pk2(-nrt[2], -nrt[3]); *(LAS u32x4_t*)(slot + RWS_KNI + 16 * lane) = o; }
;                     LDS_WAIT(); asm volatile("" ::: "memory");
;                     *(LAS f32x4*)(tmp + RWT_NM + (fr * 16 + 4 * fq) * 4) = nac;
;                     LDS_WAIT(); asm volatile("" ::: "memory");
;                     float Tc[16];
;                     f32x4 nvv[16][4];
;     ...
;                     RW_LD_ROWS(1, 8) RW_LD_ROWS(9, 12)
;                     asm volatile("" ::: "memory");
;                     RW_DO_ROWS(0, 8)
;                     RW_LD_ROWS(13, 15)
;                     asm volatile("" ::: "memory");
;                     RW_DO_ROWS(9, 12)
;                     RW_DO_ROWS(13, 15)
	v_mfma_f32_16x16x32_bf16 v[76:79], v[32:35], v[64:67], 0
	v_mov_b32_e32 v10, s93
	v_add_u32_e32 v199, s74, v27
	s_or_b64 vcc, s[64:65], s[48:49]
	s_waitcnt lgkmcnt(1)
	v_mfma_f32_16x16x32_bf16 v[32:35], v[32:35], v[88:91], 0
	v_mov_b32_e32 v237, v236
	v_mfma_f32_16x16x32_bf16 v[64:67], v[80:83], v[64:67], 0
	v_mfma_f32_16x16x32_bf16 v[80:83], v[80:83], v[88:91], 0
	s_waitcnt lgkmcnt(0)
	v_mfma_f32_16x16x32_bf16 v[32:35], v[72:75], v[92:95], v[32:35]
	v_mfma_f32_16x16x32_bf16 v[76:79], v[72:75], v[68:71], v[76:79]
	v_mov_b32_e32 v72, s93
	s_nop 5
	v_cndmask_b32_e64 v11, v32, v72, s[50:51]
	v_mfma_f32_16x16x32_bf16 v[72:75], v[84:87], v[92:95], v[80:83]
	v_mfma_f32_16x16x32_bf16 v[64:67], v[84:87], v[68:71], v[64:67]
	v_cndmask_b32_e64 v71, 0, v79, s[54:55]
	s_nop 5
	v_cndmask_b32_e64 v10, v72, v10, s[50:51]
	v_cndmask_b32_e64 v10, v10, v72, s[48:49]
	v_cndmask_b32_e64 v72, 0, v73, s[48:49]
	v_cvt_pk_bf16_f32 v72, v10, v72
	v_cndmask_b32_e64 v10, v11, v32, s[48:49]
	v_cndmask_b32_e64 v11, 0, v33, s[48:49]
	v_cndmask_b32_e64 v73, v74, 0, s[52:53]
	v_cndmask_b32_e64 v74, v75, 0, s[56:57]
	v_xor_b32_e32 v10, 0x80000000, v10
	v_xor_b32_e32 v11, 0x80000000, v11
	v_cvt_pk_bf16_f32 v73, v73, v74
	v_cvt_pk_bf16_f32 v74, v10, v11
	v_cndmask_b32_e64 v10, v34, 0, s[52:53]
	v_xor_b32_e32 v10, 0x80000000, v10
	v_cndmask_b32_e64 v11, -v35, v251, s[56:57]
	v_cvt_pk_bf16_f32 v75, v10, v11
	ds_write_b128 v199, v[72:75] offset:8448
	v_cndmask_b32_e64 v70, 0, v78, s[62:63]
	v_cndmask_b32_e64 v69, 0, v77, s[64:65]
	v_cndmask_b32_e32 v68, 0, v76, vcc
	ds_write_b128 v195, v[68:71]
	v_mov_b32_e32 v10, s90
	ds_read_b128 v[32:35], v10 offset:64
	ds_read_b128 v[68:71], v10 offset:128
	ds_read_b128 v[70:73], v10 offset:192
	ds_read_b128 v[74:77], v10 offset:256
	ds_read_b128 v[78:81], v10 offset:320
	ds_read_b128 v[82:85], v10 offset:336
	ds_read_b128 v[84:87], v10 offset:384
	ds_read_b128 v[88:91], v10 offset:400
	ds_read_b128 v[90:93], v10 offset:448
	ds_read_b128 v[94:97], v10 offset:464
	ds_read_b128 v[98:101], v10 offset:512
	ds_read_b128 v[102:105], v10 offset:528
	ds_read_b128 v[106:109], v10 offset:576
	s_waitcnt lgkmcnt(12)
	ds_read_b128 v[110:113], v10 offset:592
	ds_read_b128 v[114:117], v10 offset:608
	s_waitcnt lgkmcnt(12)
	v_fma_f32 v11, -v162, v32, v163
	v_fma_f32 v32, -v162, v68, v180
	ds_read_b128 v[116:119], v10 offset:640
	ds_read_b128 v[120:123], v10 offset:656
	ds_read_b128 v[124:127], v10 offset:672
	s_waitcnt lgkmcnt(3)
	v_fma_f32 v115, -v69, v11, v32
	v_fma_f32 v32, -v162, v70, v181
	ds_read_b128 v[126:129], v10 offset:704
	ds_read_b128 v[130:133], v10 offset:720
	ds_read_b128 v[134:137], v10 offset:736
	ds_read_b128 v[164:167], v10 offset:768
	ds_read_b128 v[168:171], v10 offset:784
	ds_read_b128 v[172:175], v10 offset:800
	v_fma_f32 v32, -v71, v11, v32
	s_waitcnt lgkmcnt(3)
	v_fma_f32 v137, -v72, v115, v32
	v_fma_f32 v32, -v162, v74, v182
	v_fma_f32 v32, -v11, v75, v32
	v_fma_f32 v32, -v76, v115, v32
	v_fma_f32 v200, -v77, v137, v32
	v_fma_f32 v32, -v162, v78, v183
	v_fma_f32 v32, -v11, v79, v32
	v_fma_f32 v32, -v80, v115, v32
	v_fma_f32 v32, -v81, v137, v32
	v_fma_f32 v201, -v82, v200, v32
	v_fma_f32 v32, -v162, v84, v184
	v_fma_f32 v32, -v11, v85, v32
	v_fma_f32 v32, -v115, v86, v32
	v_fma_f32 v32, -v87, v137, v32
	v_fma_f32 v32, -v88, v200, v32
	v_fma_f32 v202, -v89, v201, v32
	v_fma_f32 v32, -v162, v90, v185
	v_fma_f32 v32, -v11, v91, v32
	v_fma_f32 v32, -v115, v92, v32
	v_fma_f32 v32, -v137, v93, v32
	v_fma_f32 v32, -v200, v94, v32
	v_fma_f32 v32, -v95, v201, v32
	v_fma_f32 v203, -v96, v202, v32
	v_fma_f32 v32, -v162, v98, v186
	v_fma_f32 v32, -v11, v99, v32
	v_fma_f32 v32, -v115, v100, v32
	v_fma_f32 v32, -v137, v101, v32
	v_fma_f32 v32, -v200, v102, v32
	v_fma_f32 v32, -v201, v103, v32
	v_fma_f32 v32, -v104, v202, v32
	v_fma_f32 v104, -v105, v203, v32
	ds_read_b128 v[32:35], v10 offset:832
	ds_read_b128 v[68:71], v10 offset:848
	ds_read_b128 v[72:75], v10 offset:864
	ds_read_b128 v[76:79], v10 offset:880
	ds_read_b128 v[78:81], v10 offset:896
	ds_read_b128 v[82:85], v10 offset:912
	ds_read_b128 v[86:89], v10 offset:928
	ds_read_b128 v[90:93], v10 offset:944
	ds_read_b128 v[92:95], v10 offset:960
	ds_read_b128 v[96:99], v10 offset:976
	ds_read_b128 v[100:103], v10 offset:992
	ds_read_b128 v[176:179], v10 offset:1008
	s_waitcnt lgkmcnt(7)
	v_fma_f32 v10, -v162, v106, v187
	v_fma_f32 v77, -v162, v116, v188
	v_fma_f32 v105, -v162, v126, v189
	v_fma_f32 v106, -v162, v164, v190
	v_fma_f32 v32, -v162, v32, v191
	v_fma_f32 v10, -v11, v107, v10
	v_fma_f32 v77, -v11, v117, v77
	v_fma_f32 v105, -v11, v127, v105
	v_fma_f32 v106, -v11, v165, v106
	v_fma_f32 v32, -v11, v33, v32
	v_fma_f32 v10, -v115, v108, v10
	v_fma_f32 v77, -v115, v118, v77
	v_fma_f32 v105, -v115, v128, v105
	v_fma_f32 v106, -v115, v166, v106
	v_fma_f32 v32, -v115, v34, v32
	v_fma_f32 v10, -v137, v109, v10
	v_fma_f32 v77, -v137, v119, v77
	v_fma_f32 v105, -v137, v129, v105
	v_fma_f32 v106, -v137, v167, v106
	v_fma_f32 v32, -v137, v35, v32
	v_fma_f32 v33, -v162, v78, v192
	s_waitcnt lgkmcnt(3)
; #define LAS __attribute__((address_space(3)))
; __device__ __forceinline__ void rw_scan(const bf16* R, const bf16* K, const bf16* V, const bf16* WM, const bf16* A, const float* k_k, const float* k_a, bf16* Y, LAS unsigned char* lds) {
;     ...
;                     RW_DO_ROWS(0, 8)
;                     RW_LD_ROWS(13, 15)
;                     asm volatile("" ::: "memory");
;                     RW_DO_ROWS(9, 12)
;                     RW_DO_ROWS(13, 15)
;     ...
; #pragma unroll
;                     for (int e = 0; e < 4; ++e) {
;                         float tv = Tc[0];
; #pragma unroll
;                         for (int s = 0; s < 16; ++s) if (s == 4 * fq + e) tv = Tc[s];
;                         *(LAS unsigned short*)(tmp + RWT_TM + ((4 * fq + e) * 16 + fr) * 2) = (unsigned short)f2bf(tv);
;                     }
;                     LDS_WAIT(); asm volatile("" ::: "memory");
;                     const v2u tq = lds_8(tmp + RWT_TM + (fr * 16 + 4 * fq) * 2);
;                     const bf16x8 opT = mk8(tq.x, tq.y, 0u, 0u);
;                     f32x4 xac = __builtin_amdgcn_mfma_f32_16x16x32_bf16(mk8(pk2(kat[0], kat[1]), pk2(kat[2], kat[3]), 0u, 0u), mk8(vlo, vhi, 0u, 0u), (f32x4){0.f, 0.f, 0.f, 0.f}, 0, 0, 0);
;                     const f32x4 wvv = __builtin_amdgcn_mfma_f32_16x16x32_bf16(opT, mk8(pk2(xac[0], xac[1]), pk2(xac[2], xac[3]), 0u, 0u), (f32x4){0.f, 0.f, 0.f, 0.f}, 0, 0, 0);
;                     *(LAS f32x4*)(slot + RWS_WVI + 16 * lane) = wvv;
;                     f32x4 aht[4];
; #pragma unroll
;                     for (int nt = 0; nt < 4; ++nt) {
;                         const v2u ab = lds_8(tmp + RWT_ABT + rwz(16 * nt + fr) * 32 + 8 * fq);
;                         aht[nt] = __builtin_amdgcn_mfma_f32_16x16x32_bf16(mk8(ab.x, ab.y, 0u, 0u), opT, (f32x4){0.f, 0.f, 0.f, 0.f}, 0, 0, 0);
;                     }
; #pragma unroll
;                     for (int p = 0; p < 2; ++p) { u32x4_t o; o.x = pk2(aht[2 * p][0], aht[2 * p][1]); o.y = pk2(aht[2 * p][2], aht[2 * p][3]); o.z = pk2(aht[2 * p + 1][0], aht[2 * p + 1][1]); o.w = pk2(aht[2 * p + 1][2], aht[2 * p + 1][3]);
;                         *(LAS u32x4_t*)(slot + RWS_AH + (p * 64 + lane) * 16) = o; }
;                     LDS_WAIT(); asm volatile("" ::: "memory");
;                     if (lane == 0) flg[cj % RW_NSLOT] = (unsigned)(cj + 1);
	v_fma_f32 v34, -v162, v92, v193
	v_fma_f32 v10, -v200, v110, v10
	v_fma_f32 v77, -v200, v120, v77
	v_fma_f32 v105, -v200, v130, v105
	v_fma_f32 v106, -v200, v168, v106
	v_fma_f32 v32, -v200, v68, v32
	v_fma_f32 v33, -v11, v79, v33
	v_fma_f32 v34, -v11, v93, v34
	v_fma_f32 v10, -v201, v111, v10
	v_fma_f32 v77, -v201, v121, v77
	v_fma_f32 v105, -v201, v131, v105
	v_fma_f32 v106, -v201, v169, v106
	v_fma_f32 v32, -v201, v69, v32
	v_fma_f32 v33, -v115, v80, v33
	v_fma_f32 v34, -v115, v94, v34
	v_fma_f32 v10, -v112, v202, v10
	v_fma_f32 v77, -v202, v122, v77
	v_fma_f32 v105, -v202, v132, v105
	v_fma_f32 v106, -v202, v170, v106
	v_fma_f32 v32, -v202, v70, v32
	v_fma_f32 v33, -v137, v81, v33
	v_fma_f32 v34, -v137, v95, v34
	v_fma_f32 v10, -v113, v203, v10
	v_fma_f32 v77, -v123, v203, v77
	v_fma_f32 v105, -v203, v133, v105
	v_fma_f32 v106, -v203, v171, v106
	v_fma_f32 v32, -v203, v71, v32
	v_fma_f32 v33, -v200, v82, v33
	s_waitcnt lgkmcnt(2)
	v_fma_f32 v34, -v200, v96, v34
	v_fma_f32 v10, -v114, v104, v10
	v_fma_f32 v77, -v124, v104, v77
	v_fma_f32 v105, -v104, v134, v105
	v_fma_f32 v106, -v104, v172, v106
	v_fma_f32 v32, -v104, v72, v32
	v_fma_f32 v33, -v201, v83, v33
	v_fma_f32 v34, -v201, v97, v34
	v_fma_f32 v77, -v125, v10, v77
	v_fma_f32 v105, -v135, v10, v105
	v_fma_f32 v106, -v10, v173, v106
	v_fma_f32 v32, -v10, v73, v32
	v_fma_f32 v33, -v202, v84, v33
	v_fma_f32 v34, -v202, v98, v34
	v_fma_f32 v105, -v136, v77, v105
	v_fma_f32 v106, -v174, v77, v106
	v_fma_f32 v32, -v77, v74, v32
	v_fma_f32 v33, -v203, v85, v33
	v_fma_f32 v34, -v203, v99, v34
	v_cndmask_b32_e64 v11, v162, v11, s[42:43]
	v_fma_f32 v106, -v175, v105, v106
	v_fma_f32 v32, -v75, v105, v32
	v_fma_f32 v33, -v104, v86, v33
	s_waitcnt lgkmcnt(1)
	v_fma_f32 v34, -v104, v100, v34
	v_cndmask_b32_e64 v11, v11, v201, s[58:59]
	v_fma_f32 v32, -v76, v106, v32
	v_fma_f32 v33, -v10, v87, v33
	v_fma_f32 v34, -v10, v101, v34
	v_cndmask_b32_e64 v10, v11, v10, s[60:61]
	v_cndmask_b32_e64 v10, v10, v32, s[46:47]
	v_fma_f32 v33, -v77, v88, v33
	v_cvt_pk_bf16_f32 v10, v10, s0
	v_fma_f32 v33, -v105, v89, v33
	ds_write_b16 v196, v10 offset:2080
	v_cndmask_b32_e64 v10, v162, v115, s[42:43]
	v_fma_f32 v33, -v90, v106, v33
	v_cndmask_b32_e64 v10, v10, v202, s[58:59]
	v_fma_f32 v33, -v91, v32, v33
	v_cndmask_b32_e64 v10, v10, v77, s[60:61]
	v_fma_f32 v34, -v77, v102, v34
	v_cndmask_b32_e64 v10, v10, v33, s[46:47]
	v_fma_f32 v34, -v105, v103, v34
	v_cvt_pk_bf16_f32 v10, v10, s0
	s_waitcnt lgkmcnt(1)
	v_fma_f32 v34, -v106, v176, v34
	ds_write_b16 v196, v10 offset:2112
	v_cndmask_b32_e64 v10, v162, v137, s[42:43]
	v_fma_f32 v34, -v177, v32, v34
	v_cndmask_b32_e64 v35, v162, v200, s[58:59]
	v_cndmask_b32_e64 v10, v10, v203, s[58:59]
	v_fma_f32 v34, -v178, v33, v34
	v_cndmask_b32_e64 v35, v35, v104, s[60:61]
	v_cndmask_b32_e64 v10, v10, v105, s[60:61]
	v_cndmask_b32_e64 v35, v35, v106, s[46:47]
	v_cndmask_b32_e64 v10, v10, v34, s[46:47]
	v_cvt_pk_bf16_f32 v35, v35, s0
	v_cvt_pk_bf16_f32 v10, v10, s0
	ds_write_b16 v196, v35 offset:2048
	ds_write_b16 v196, v10 offset:2144
	v_cndmask_b32_e64 v10, 0, v67, s[54:55]
	v_cndmask_b32_e64 v11, 0, v66, s[62:63]
	v_cndmask_b32_e64 v32, 0, v65, s[64:65]
	v_cndmask_b32_e32 v33, 0, v64, vcc
	v_cvt_pk_bf16_f32 v32, v33, v32
	v_cvt_pk_bf16_f32 v33, v11, v10
	v_mov_b32_e32 v34, v236
	v_mov_b32_e32 v35, v236
	ds_read_b64 v[234:235], v197 offset:2048
	v_mov_b32_e32 v10, v236
	v_mov_b32_e32 v11, v236
	v_mov_b32_e32 v66, v236
	v_mov_b32_e32 v67, v236
	v_mfma_f32_16x16x32_bf16 v[8:11], v[32:35], v[8:11], 0
	v_add_u32_e32 v32, v148, v151
	v_add_u32_e32 v34, v148, v152
	v_add_u32_e32 v35, v148, v153
	v_mov_b32_e32 v70, v236
	v_mov_b32_e32 v71, v236
	s_nop 2
	v_cvt_pk_bf16_f32 v8, v8, v9
	v_cvt_pk_bf16_f32 v9, v10, v11
	v_mov_b32_e32 v10, v236
	v_mov_b32_e32 v11, v236
	s_waitcnt lgkmcnt(0)
	s_nop 0
	v_mfma_f32_16x16x32_bf16 v[8:11], v[234:237], v[8:11], 0
	s_nop 7
	ds_write_b128 v199, v[8:11] offset:9472
	v_add_u32_e32 v8, v148, v150
	ds_read_b64 v[8:9], v8 offset:6144
	v_mov_b32_e32 v10, v236
	v_mov_b32_e32 v11, v236
	ds_read_b64 v[32:33], v32 offset:6144
	ds_read_b64 v[64:65], v34 offset:6144
	ds_read_b64 v[68:69], v35 offset:6144
	v_mov_b32_e32 v34, v236
	v_mov_b32_e32 v35, v236
	s_waitcnt lgkmcnt(3)
	v_mfma_f32_16x16x32_bf16 v[8:11], v[8:11], v[234:237], 0
	s_waitcnt lgkmcnt(2)
	v_mfma_f32_16x16x32_bf16 v[32:35], v[32:35], v[234:237], 0
	s_nop 5
	v_cvt_pk_bf16_f32 v8, v8, v9
	v_cvt_pk_bf16_f32 v9, v10, v11
	s_waitcnt lgkmcnt(1)
	v_mfma_f32_16x16x32_bf16 v[64:67], v[64:67], v[234:237], 0
	s_waitcnt lgkmcnt(0)
	v_mfma_f32_16x16x32_bf16 v[68:71], v[68:71], v[234:237], 0
	v_cvt_pk_bf16_f32 v10, v32, v33
	v_cvt_pk_bf16_f32 v11, v34, v35
	ds_write_b128 v199, v[8:11]
	s_nop 2
	v_cvt_pk_bf16_f32 v8, v64, v65
	v_cvt_pk_bf16_f32 v9, v66, v67
	v_cvt_pk_bf16_f32 v10, v68, v69
	v_cvt_pk_bf16_f32 v11, v70, v71
	ds_write_b128 v199, v[8:11] offset:1024
	s_waitcnt lgkmcnt(0)
	s_and_saveexec_b64 s[68:69], s[40:41]
	s_cbranch_execz .LBB0_495
	s_lshl_b32 s75, s92, 2
	s_add_i32 s75, s75, 0
	s_add_i32 s74, s89, 1
	s_add_i32 s75, s75, 0x26c00
	v_mov_b32_e32 v8, s75
	v_mov_b32_e32 v9, s74
	ds_write_b32 v8, v9
	s_branch .LBB0_495
